# v31 + GLA prep: gate weights/biases (invariant across a workgroup's items) loaded once per phase into a resident register bank; later items skip the 34 loads and their address arithmetic
# speedup vs baseline: 1.0097x; 1.0048x over previous
; __device__ __forceinline__ int TIDX() { int t = threadIdx.x; asm volatile("" : "+v"(t)); return t; }
; __device__ __forceinline__ char* opaque(char* q) { size_t z = 0; asm volatile("" : "+s"(z)); return q + z; }
; __device__ __forceinline__ int BIDX() { int b = blockIdx.x; asm volatile("" : "+s"(b)); return b; }
; LPHASE void phase_gla_prep(char* ws_, const float* x_, float* out_, const float* meta_, int nseq_, char* lds) {
;   const int tid0 = TIDX();
;   char* wsp = opaque(ws_);
;   const bf16_t* b2 = (const bf16_t*)(wsp + O_B2); const bf16_t* b4 = (const bf16_t*)(wsp + O_B4);
;   char* gp = wsp + O_GP;
;   float* lgF = (float*)lds; float* lgB = lgF + 64 * LGP;
;   char* R2 = lds + 2 * 64 * LGP * 4;
;   bf16_t* qhF = (bf16_t*)R2; bf16_t* khF = qhF + 64 * 128; bf16_t* qhB = khF + 64 * 128; bf16_t* khB = qhB + 64 * 128;
;   float* af = (float*)R2;
;   bf16_t* vt = (bf16_t*)(R2 + 8192);
;   float* tot = (float*)(R2 + 65536);
;   const float* smg = (const float*)(wsp + O_SMALL);
;   const int nmeta = 4 * nseq_, bid = BIDX();
;   for (int kk = (bid < nmeta ? -1 : 0); ; ++kk) {
;     const int it = kk < 0 ? 1024 + bid : bid + kk * (int)gridDim.x;
;     if (kk >= 0 && it >= 1024) break;
.LBB0_491:
	s_andn2_b64 vcc, exec, s[2:3]
	s_mov_b64 s[2:3], 0
	v_writelane_b32 v255, s2, 27
	s_mov_b64 s[58:59], 0
	s_mov_b64 s[68:69], 0
	v_writelane_b32 v255, s3, 28
	s_cbranch_vccnz .LBB0_556
	v_readlane_b32 s76, v254, 36
	v_readlane_b32 s78, v253, 31
	s_mov_b32 s70, 0x3b800000
	s_cmp_lt_i32 s49, 2
	s_mov_b64 s[0:1], -1
	v_readlane_b32 s77, v254, 37
	v_readlane_b32 s79, v253, 32
	s_mov_b32 s71, 0x3aaaaaab
	s_movk_i32 s72, 0x2000
	s_movk_i32 s73, 0x3000
	s_movk_i32 s74, 0x5000
	s_movk_i32 s75, 0x7000
	s_movk_i32 s83, 0x210
	s_mov_b32 s84, 0x5040100
	v_readlane_b32 s85, v254, 33
	s_cbranch_scc1 .LBB0_539
	s_cmp_gt_i32 s49, 2
	s_movk_i32 s69, 0x6000
	s_cbranch_scc0 .LBB0_532
	v_mov_b32_e32 v26, v135
	s_mov_b64 s[2:3], 0
	s_lshl_b32 s0, s51, 2
	v_readlane_b32 s40, v253, 0
	s_cmp_lt_i32 s40, s0
	s_cselect_b64 s[0:1], -1, 0
	s_and_b64 s[24:25], s[0:1], exec
	s_cselect_b32 s12, 0x400, 0
	s_add_i32 s12, s12, s40
	s_cmpk_lt_i32 s12, 0x400
	s_cselect_b64 s[24:25], -1, 0
	s_or_b64 s[24:25], s[0:1], s[24:25]
	s_andn2_b64 vcc, exec, s[24:25]
	s_cbranch_vccnz .LBB0_531
	s_add_u32 s2, s80, s2
	s_addc_u32 s3, s81, s3
	s_add_u32 s24, s2, 0x18c32000
	s_addc_u32 s25, s3, 0
	s_add_u32 s41, s2, 0x8640000
	s_addc_u32 s48, s3, 0
	s_add_u32 s34, s2, 0x1f572000
	s_addc_u32 s35, s3, 0
	s_add_u32 s36, s2, 0x1ed32080
	s_addc_u32 s37, s3, 0
	s_add_u32 s52, s2, 0xd6e0000
	s_addc_u32 s53, s3, 0
	s_add_u32 s62, s2, 0xf720000
	s_addc_u32 s63, s3, 0
	s_add_u32 s64, s2, 0xa680000
	s_addc_u32 s65, s3, 0
	s_add_u32 s66, s2, 0xc6c0000
	v_cndmask_b32_e64 v0, 0, -1, s[0:1]
	s_addc_u32 s67, s3, 0
	v_readfirstlane_b32 s68, v0
	s_mov_b32 s32, 0
	s_branch .LBB0_497

; LPHASE void phase_gla_prep(char* ws_, const float* x_, float* out_, const float* meta_, int nseq_, char* lds) {
;     ...
;     { bf16_t* dst = (bf16_t*)(gp + GP_VT) + ((size_t)ch * 4 + hd) * 256 * 64;
; #pragma unroll
;       for (int q = 0; q < 4; ++q) { const int i8 = (tid & 7) * 8, c = (tid >> 3) + 64 * q; bf16x8 w;
; #pragma unroll
;         for (int e = 0; e < 8; ++e) w[e] = (short)vt[(i8 + e) * 264 + c];
;         *(bf16x8*)(dst + c * 64 + i8) = w; } }
;     { float wf[16], wb[16];
; #pragma unroll
;       for (int k = 0; k < 16; ++k) { wf[k] = smg[S_WAF + k * 512 + hd * 128 + d]; wb[k] = smg[S_WAB + k * 512 + hd * 128 + d]; }
.LBB0_505:
	s_or_b64 exec, exec, s[28:29]
	s_ashr_i32 s1, s0, 31
	s_lshl_b64 s[38:39], s[0:1], 2
	s_or_b32 s38, s38, s30
	v_lshlrev_b32_e32 v0, 3, v16
	s_lshl_b64 s[2:3], s[38:39], 15
	s_add_u32 s0, s52, s2
	v_and_b32_e32 v0, 56, v0
	s_addc_u32 s1, s53, s3
	v_ashrrev_i32_e32 v1, 3, v16
	v_lshlrev_b32_e32 v132, 1, v0
	v_lshl_add_u64 v[8:9], s[0:1], 0, v[132:133]
	v_mul_u32_u24_e32 v4, 0x210, v0
	v_lshlrev_b32_e32 v5, 1, v1
	v_readlane_b32 s0, v254, 31
	s_waitcnt lgkmcnt(0)
	s_barrier
	v_add3_u32 v4, s0, v5, v4
	ds_read_u16 v5, v4 offset:3168
	ds_read_u16 v6, v4 offset:3696
	ds_read_u16 v12, v4 offset:3296
	ds_read_u16 v13, v4 offset:3824
	ds_read_u16 v14, v4 offset:3424
	ds_read_u16 v15, v4 offset:3952
	ds_read_u16 v17, v4 offset:4080
	ds_read_u16 v22, v4 offset:3552
	s_waitcnt lgkmcnt(6)
	v_perm_b32 v7, v6, v5, s84
	ds_read_u16 v5, v4 offset:2112
	ds_read_u16 v6, v4 offset:2640
	ds_read_u16 v18, v4 offset:2240
	ds_read_u16 v19, v4 offset:2768
	ds_read_u16 v23, v4 offset:2368
	ds_read_u16 v24, v4 offset:2896
	ds_read_u16 v25, v4 offset:3024
	ds_read_u16 v60, v4 offset:2496
	s_waitcnt lgkmcnt(6)
	v_perm_b32 v6, v6, v5, s84
	ds_read_u16 v5, v4 offset:1056
	ds_read_u16 v10, v4 offset:1584
	ds_read_u16 v61, v4 offset:1184
	ds_read_u16 v62, v4 offset:1712
	ds_read_u16 v63, v4 offset:1312
	ds_read_u16 v64, v4 offset:1840
	ds_read_u16 v65, v4 offset:1968
	ds_read_u16 v66, v4 offset:1440
	v_lshlrev_b32_e32 v20, 6, v1
	s_waitcnt lgkmcnt(6)
	v_perm_b32 v5, v10, v5, s84
	ds_read_u16 v10, v4
	ds_read_u16 v11, v4 offset:528
	ds_read_u16 v67, v4 offset:128
	ds_read_u16 v68, v4 offset:656
	ds_read_u16 v69, v4 offset:256
	ds_read_u16 v70, v4 offset:784
	ds_read_u16 v71, v4 offset:912
	ds_read_u16 v72, v4 offset:384
	v_ashrrev_i32_e32 v21, 31, v20
	s_waitcnt lgkmcnt(6)
	v_perm_b32 v4, v11, v10, s84
	v_lshl_add_u64 v[10:11], v[20:21], 1, v[8:9]
	global_store_dwordx4 v[10:11], v[4:7], off
	s_add_i32 s0, s12, 0x980
	v_mov_b32_e32 v84, 0
	v_perm_b32 v6, v19, v18, s84
	v_add_u32_e32 v18, 0x1000, v20
	v_ashrrev_i32_e32 v19, 31, v18
	v_perm_b32 v7, v13, v12, s84
	v_perm_b32 v5, v62, v61, s84
	s_waitcnt lgkmcnt(4)
	v_perm_b32 v4, v68, v67, s84
	v_lshl_add_u64 v[10:11], v[18:19], 1, v[8:9]
	global_store_dwordx4 v[10:11], v[4:7], off
	v_add_u32_e32 v10, 0x2000, v20
	v_ashrrev_i32_e32 v11, 31, v10
	v_perm_b32 v7, v15, v14, s84
	v_perm_b32 v6, v24, v23, s84
	v_perm_b32 v5, v64, v63, s84
	s_waitcnt lgkmcnt(2)
	v_perm_b32 v4, v70, v69, s84
	v_lshl_add_u64 v[10:11], v[10:11], 1, v[8:9]
	global_store_dwordx4 v[10:11], v[4:7], off
	v_add_u32_e32 v10, 0x3000, v20
	v_ashrrev_i32_e32 v11, 31, v10
	v_perm_b32 v7, v17, v22, s84
	v_perm_b32 v6, v25, v60, s84
	v_perm_b32 v5, v65, v66, s84
	s_waitcnt lgkmcnt(0)
	v_perm_b32 v4, v71, v72, s84
	v_lshl_add_u64 v[8:9], v[10:11], 1, v[8:9]
	global_store_dwordx4 v[8:9], v[4:7], off
	s_cmp_eq_u32 s32, 1
	s_cbranch_scc1 .Lw_skip
	s_mov_b32 s32, 1
	v_mov_b32_e32 v25, v133
	s_nop 0
	v_or_b32_e32 v4, s0, v2
	v_lshlrev_b32_e32 v132, 2, v4
	v_lshl_add_u64 v[22:23], s[34:35], 0, v[132:133]
	s_add_i32 s0, s12, 0x2b80
	v_add_co_u32_e32 v70, vcc, s4, v22
	v_or_b32_e32 v5, s0, v2
	s_nop 0
	v_addc_co_u32_e32 v71, vcc, 0, v23, vcc
	v_lshlrev_b32_e32 v24, 2, v5
	v_add_co_u32_e32 v6, vcc, s72, v22
	v_lshl_add_u64 v[60:61], s[34:35], 0, v[24:25]
	s_nop 0
	v_addc_co_u32_e32 v7, vcc, 0, v23, vcc
	v_add_co_u32_e32 v72, vcc, s4, v60
	s_add_i32 s0, s12, 0x2980
	s_nop 0
	v_addc_co_u32_e32 v73, vcc, 0, v61, vcc
	v_add_co_u32_e32 v4, vcc, s72, v60
	s_addk_i32 s12, 0x4b80
	s_nop 0
	v_addc_co_u32_e32 v5, vcc, 0, v61, vcc
	v_add_co_u32_e32 v14, vcc, s92, v22
	v_or_b32_e32 v25, s12, v2
	s_nop 0
	v_addc_co_u32_e32 v15, vcc, 0, v23, vcc
	v_add_co_u32_e32 v74, vcc, s73, v22
	global_load_dword v172, v[6:7], off offset:-4096
	global_load_dword v173, v[4:5], off offset:-4096
	global_load_dword v176, v[6:7], off
	global_load_dword v177, v[4:5], off
	global_load_dword v179, v[4:5], off offset:2048
	global_load_dword v180, v[14:15], off offset:-4096
	s_nop 0
	global_load_dword v184, v[14:15], off
	global_load_dword v178, v[6:7], off offset:2048
	v_addc_co_u32_e32 v75, vcc, 0, v23, vcc
	v_add_co_u32_e32 v76, vcc, s73, v60
	v_or_b32_e32 v17, s0, v2
	s_nop 0
	v_addc_co_u32_e32 v77, vcc, 0, v61, vcc
	v_add_co_u32_e32 v8, vcc, s92, v60
	v_lshlrev_b32_e32 v17, 2, v17
	s_nop 0
	v_addc_co_u32_e32 v9, vcc, 0, v61, vcc
	v_add_co_u32_e32 v78, vcc, s69, v22
	s_movk_i32 s0, 0x2040
	s_nop 0
	v_addc_co_u32_e32 v79, vcc, 0, v23, vcc
	v_add_co_u32_e32 v80, vcc, s69, v60
	s_mov_b32 s12, 0
	s_nop 0
	v_addc_co_u32_e32 v81, vcc, 0, v61, vcc
	global_load_dword v181, v[8:9], off offset:-4096
	global_load_dword v185, v[8:9], off
	global_load_dword v187, v[8:9], off offset:2048
	s_nop 0
	global_load_dword v188, v[78:79], off offset:-4096
	global_load_dword v189, v[80:81], off offset:-4096
	global_load_dword v192, v[78:79], off
	global_load_dword v194, v[78:79], off offset:2048
	global_load_dword v186, v[14:15], off offset:2048
	v_add_co_u32_e32 v78, vcc, s74, v22
	global_load_dword v193, v[80:81], off
	global_load_dword v195, v[80:81], off offset:2048
	v_addc_co_u32_e32 v79, vcc, 0, v23, vcc
	v_add_co_u32_e32 v82, vcc, s74, v60
	s_nop 1
	v_addc_co_u32_e32 v83, vcc, 0, v61, vcc
	v_add_co_u32_e32 v80, vcc, s75, v22
	s_nop 1
	v_addc_co_u32_e32 v81, vcc, 0, v23, vcc
	v_add_co_u32_e32 v60, vcc, s75, v60
	global_load_dword v174, v[70:71], off offset:2048
	s_nop 0
	global_load_dword v175, v[72:73], off offset:2048
	s_nop 0
	global_load_dword v182, v[74:75], off offset:2048
	global_load_dword v183, v[76:77], off offset:2048
	global_load_dword v190, v[78:79], off offset:2048
	global_load_dword v191, v[82:83], off offset:2048
	global_load_dword v196, v[80:81], off
	global_load_dword v198, v[80:81], off offset:2048
	v_lshlrev_b32_e32 v79, 2, v25
	v_addc_co_u32_e32 v61, vcc, 0, v61, vcc
	global_load_dword v168, v132, s[34:35]
	global_load_dword v169, v24, s[34:35]
	global_load_dword v171, v24, s[34:35] offset:2048
	global_load_dword v170, v132, s[34:35] offset:2048
	s_nop 0
	global_load_dword v197, v[60:61], off
	global_load_dword v199, v[60:61], off offset:2048
	global_load_dword v200, v17, s[34:35]
	s_nop 0
	global_load_dword v201, v79, s[34:35]
; LPHASE void phase_gla_prep(char* ws_, const float* x_, float* out_, const float* meta_, int nseq_, char* lds) {
;     ...
;       const float bfv = smg[S_BAF + hd * 128 + d], bbv = smg[S_BAB + hd * 128 + d];
;       float tfl = 0.f, tbl = 0.f;
; #pragma unroll 2
;       for (int ii = 0; ii < 16; ++ii) { const int i = ig * 16 + ii; float sf = bfv, sb = bbv; const float* a = af + i * 32;
; #pragma unroll
;         for (int k = 0; k < 16; ++k) { sf += a[k] * wf[k]; sb += a[16 + k] * wb[k]; }
;         float lf = (fminf(sf, 0.f) - __logf(1.f + __expf(-fabsf(sf)))) * (1.f / 16.f), lb = (fminf(sb, 0.f) - __logf(1.f + __expf(-fabsf(sb)))) * (1.f / 16.f);
;         if (ismeta && i >= 16) { lf = 0.f; lb = 0.f; }
;         lgF[i * LGP + d] = lf; lgB[i * LGP + d] = lb; tfl += lf; tbl += lb; }
.Lw_skip:
	s_movk_i32 s0, 0x2040
	s_mov_b32 s12, 0
	v_lshlrev_b32_e32 v17, 4, v49
	v_lshlrev_b32_e32 v60, 11, v49
	v_mul_lo_u32 v81, v49, s0
	v_lshlrev_b32_e32 v61, 2, v2
	v_add_u32_e32 v80, 0, v60
	v_add3_u32 v81, v81, v61, 0
	v_mov_b32_e32 v83, 0
	v_mov_b32_e32 v82, v17
.LBB0_506:
	v_add_u32_e32 v85, s12, v80
	v_add_u32_e32 v96, 0x10200, v85
	ds_read_b128 v[100:103], v96
	ds_read_b128 v[104:107], v96 offset:64
	ds_read_b128 v[108:111], v96 offset:16
	ds_read_b128 v[112:115], v96 offset:80
	ds_read_b128 v[116:119], v96 offset:32
	ds_read_b128 v[120:123], v96 offset:96
	ds_read_b128 v[124:127], v96 offset:48
	ds_read_b128 v[128:131], v96 offset:112
	ds_read_b128 v[136:139], v96 offset:128
	ds_read_b128 v[140:143], v96 offset:192
	ds_read_b128 v[144:147], v96 offset:144
	ds_read_b128 v[148:151], v96 offset:208
	ds_read_b128 v[152:155], v96 offset:160
	ds_read_b128 v[156:159], v96 offset:224
	ds_read_b128 v[160:163], v96 offset:176
	ds_read_b128 v[164:167], v96 offset:240
	s_waitcnt vmcnt(0) lgkmcnt(0)
	s_addk_i32 s12, 0x100
	v_fma_f32 v94, v168, v100, v200
	v_fmac_f32_e32 v94, v170, v101
	v_fmac_f32_e32 v94, v172, v102
	v_fmac_f32_e32 v94, v174, v103
	v_fma_f32 v95, v169, v104, v201
	v_fmac_f32_e32 v95, v171, v105
	v_fmac_f32_e32 v95, v173, v106
	v_fmac_f32_e32 v95, v175, v107
	v_fmac_f32_e32 v94, v176, v108
	v_fmac_f32_e32 v94, v178, v109
	v_fmac_f32_e32 v94, v180, v110
	v_fmac_f32_e32 v94, v182, v111
	v_fmac_f32_e32 v95, v177, v112
	v_fmac_f32_e32 v95, v179, v113
	v_fmac_f32_e32 v95, v181, v114
	v_fmac_f32_e32 v95, v183, v115
	v_fma_f32 v94, v184, v116, v94
	v_fmac_f32_e32 v94, v186, v117
	v_fma_f32 v90, v185, v120, v95
	v_fmac_f32_e32 v90, v187, v121
	v_fma_f32 v91, v188, v118, v94
	v_fmac_f32_e32 v91, v190, v119
	v_fma_f32 v94, v189, v122, v90
	v_fmac_f32_e32 v94, v191, v123
	v_fma_f32 v95, v192, v124, v91
	v_fmac_f32_e32 v95, v194, v125
	v_fma_f32 v90, v193, v128, v94
	v_fmac_f32_e32 v90, v195, v129
	v_fma_f32 v88, v196, v126, v95
	v_fmac_f32_e32 v88, v198, v127
	v_fma_f32 v86, v197, v130, v90
	v_fmac_f32_e32 v86, v199, v131
	v_min_f32_e32 v87, 0, v88
	v_mul_f32_e64 v88, |v88|, s6
	v_exp_f32_e32 v88, v88
	s_nop 0
	v_add_f32_e32 v88, 1.0, v88
	v_log_f32_e32 v88, v88
	s_nop 0
	v_mul_f32_e32 v89, 0x3f317217, v88
	v_fma_f32 v89, v88, s13, -v89
	v_fmac_f32_e32 v89, 0x3377d1cf, v88
	v_fmac_f32_e32 v89, 0x3f317217, v88
	v_mov_b32_e32 v88, v89
	v_sub_f32_e32 v87, v87, v88
	v_min_f32_e32 v88, 0, v86
	v_mul_f32_e64 v86, |v86|, s6
	v_exp_f32_e32 v86, v86
	v_mul_f32_e32 v87, 0x3d800000, v87
	v_add_f32_e32 v86, 1.0, v86
	v_log_f32_e32 v86, v86
	s_nop 0
	v_mul_f32_e32 v89, 0x3f317217, v86
	v_fma_f32 v89, v86, s13, -v89
	v_fmac_f32_e32 v89, 0x3377d1cf, v86
	v_fmac_f32_e32 v89, 0x3f317217, v86
	v_mov_b32_e32 v86, v89
	v_sub_f32_e32 v86, v88, v86
	v_cmp_lt_i32_e32 vcc, 15, v82
	v_mul_f32_e32 v86, 0x3d800000, v86
	s_and_b64 s[0:1], s[26:27], vcc
	v_cndmask_b32_e64 v86, v86, 0, s[0:1]
	v_cndmask_b32_e64 v87, v87, 0, s[0:1]
	ds_write_b32 v81, v87
	ds_write_b32 v81, v86 offset:33024
	v_add_f32_e32 v84, v84, v86
	v_add_f32_e32 v83, v83, v87
	v_fma_f32 v94, v168, v136, v200
	v_fmac_f32_e32 v94, v170, v137
	v_fmac_f32_e32 v94, v172, v138
	v_fmac_f32_e32 v94, v174, v139
	v_fma_f32 v95, v169, v140, v201
	v_fmac_f32_e32 v95, v171, v141
	v_fmac_f32_e32 v95, v173, v142
	v_fmac_f32_e32 v95, v175, v143
	v_fmac_f32_e32 v94, v176, v144
	v_fmac_f32_e32 v94, v178, v145
	v_fmac_f32_e32 v94, v180, v146
	v_fmac_f32_e32 v94, v182, v147
	v_fmac_f32_e32 v95, v177, v148
	v_fmac_f32_e32 v95, v179, v149
	v_fmac_f32_e32 v95, v181, v150
	v_fmac_f32_e32 v95, v183, v151
	v_fma_f32 v94, v184, v152, v94
	v_fmac_f32_e32 v94, v186, v153
	v_fma_f32 v90, v185, v156, v95
	v_fmac_f32_e32 v90, v187, v157
	v_fma_f32 v91, v188, v154, v94
	v_fmac_f32_e32 v91, v190, v155
	v_fma_f32 v94, v189, v158, v90
	v_fmac_f32_e32 v94, v191, v159
	v_fma_f32 v95, v192, v160, v91
	v_fmac_f32_e32 v95, v194, v161
	v_fma_f32 v85, v193, v164, v94
	v_fmac_f32_e32 v85, v195, v165
	v_fma_f32 v88, v196, v162, v95
	v_fmac_f32_e32 v88, v198, v163
	v_fma_f32 v85, v197, v166, v85
	v_fmac_f32_e32 v85, v199, v167
	v_mul_f32_e64 v87, |v88|, s6
	v_exp_f32_e32 v87, v87
	v_min_f32_e32 v86, 0, v88
	v_add_f32_e32 v87, 1.0, v87
	v_log_f32_e32 v87, v87
	s_nop 0
	v_mul_f32_e32 v88, 0x3f317217, v87
	v_fma_f32 v88, v87, s13, -v88
	v_fmac_f32_e32 v88, 0x3377d1cf, v87
	v_fmac_f32_e32 v88, 0x3f317217, v87
	v_mov_b32_e32 v87, v88
	v_sub_f32_e32 v86, v86, v87
	v_min_f32_e32 v87, 0, v85
	v_mul_f32_e64 v85, |v85|, s6
	v_exp_f32_e32 v85, v85
	v_mul_f32_e32 v86, 0x3d800000, v86
	v_add_f32_e32 v85, 1.0, v85
	v_log_f32_e32 v85, v85
	s_nop 0
	v_mul_f32_e32 v88, 0x3f317217, v85
	v_fma_f32 v88, v85, s13, -v88
	v_fmac_f32_e32 v88, 0x3377d1cf, v85
	v_fmac_f32_e32 v88, 0x3f317217, v85
	v_mov_b32_e32 v85, v88
	v_sub_f32_e32 v85, v87, v85
	v_cmp_lt_i32_e32 vcc, 14, v82
	v_mul_f32_e32 v85, 0x3d800000, v85
	s_and_b64 s[0:1], s[26:27], vcc
	v_cndmask_b32_e64 v85, v85, 0, s[0:1]
	v_cndmask_b32_e64 v86, v86, 0, s[0:1]
	ds_write_b32 v81, v86 offset:516
	ds_write_b32 v81, v85 offset:33540
	v_add_f32_e32 v83, v83, v86
	v_add_f32_e32 v84, v84, v85
	v_add_u32_e32 v82, 2, v82
	v_add_u32_e32 v81, 0x408, v81
	s_cmpk_eq_i32 s12, 0x800
	s_cbranch_scc0 .LBB0_506
	v_and_b32_e32 v4, 0x3fffff80, v16
	v_lshl_add_u32 v6, v2, 2, s85
	v_lshl_add_u32 v5, v16, 2, s85
	v_lshl_add_u32 v4, v4, 2, v6
	ds_write_b32 v5, v83
	ds_write_b32 v4, v84 offset:2048
	s_waitcnt lgkmcnt(0)
	s_barrier
	ds_read2st64_b32 v[10:11], v6 offset1:2
	ds_read2st64_b32 v[8:9], v6 offset0:4 offset1:6
	ds_read2st64_b32 v[4:5], v6 offset0:8 offset1:10
	ds_read2st64_b32 v[6:7], v6 offset0:12 offset1:14
	s_movk_i32 s0, 0x80
	v_cmp_gt_u32_e32 vcc, s0, v16
	s_movk_i32 s0, 0x7f
	s_waitcnt lgkmcnt(3)
	v_add_f32_e32 v11, v10, v11
	v_cmp_lt_u32_e64 s[0:1], s0, v16
	v_mov_b32_e32 v13, 0
	s_and_saveexec_b64 s[26:27], s[0:1]
	s_cbranch_execz .LBB0_513
	v_cmp_lt_i32_e64 s[0:1], 1, v49
	s_mov_b64 s[28:29], 0
	s_and_saveexec_b64 s[30:31], s[0:1]
	s_xor_b64 s[42:43], exec, s[30:31]
	s_cbranch_execnz .LBB0_527
	s_or_saveexec_b64 s[42:43], s[42:43]
	v_mov_b32_e32 v13, v11
	s_xor_b64 exec, exec, s[42:43]
	s_cbranch_execnz .LBB0_530
